# D latent tiles: second softmax wave group skewed by 512 cycles per tile (was 256)
# baseline (speedup 1.0000x reference)
; #define LAS __attribute__((address_space(3)))
; #define ISSUE(t, KR, VR) do { const GAS bf16_t* tb_ = (const GAS bf16_t*)Z + (size_t)TILE_ROW(t) * ZW; \
;         KR[0] = *(const GAS u32x4*)(tb_ + koff); KR[1] = *(const GAS u32x4*)(tb_ + koff + 64); \
;         VR[0] = *(const GAS u32x4*)(tb_ + voff); VR[1] = *(const GAS u32x4*)(tb_ + voff + ZW); } while (0)
; DI void attn_unit_d32(const Ctx& C, const bf16_t* __restrict__ Z, bf16_t* __restrict__ Y, int b, int qsel, int hsel, bool ctxq, float lam, float post_scale, const float* subln, const float mref) {
;     ...
;     for (int t = 0; t < nt; ++t) {
;         if (t + 1 < nt) {
;             if ((t + 1) & 1) { WRITE(1, kB, vB); if (t + 3 < nt) ISSUE(t + 3, kB, vB); }
;             else { WRITE(0, kA, vA); if (t + 3 < nt) ISSUE(t + 3, kA, vA); }
;         }
;         const LAS bf16_t* Ks = lds16 + ((t & 1) * AT_BUF) / 2 + 64 * sm; const LAS bf16_t* Vt = lds16 + ((t & 1) * AT_BUF + AT_VT) / 2;
.LBB0_399:
.LBB0_407:
	v_readfirstlane_b32 s2, v208
	s_nop 0
	s_bitcmp1_b32 s2, 8
	s_cbranch_scc0 .Ldskew_a
	s_sleep 8
